# expert-table quantization split re-tuned: 10/16 of the rows at the start of P6 (odd slots), 6/16 at the end (even slots)
# speedup vs baseline: 1.0058x; 1.0058x over previous
; DI void phase7(const Params& P, char* smem) {
;     ...
;   for (int row = VB * 4 + wid; row < 2 * 16384; row += NVB * 4) {
;     const bool isv = row >= 16384; const int e = row & 16383;
;     const float* src = (isv ? P.pv : P.pu) + (long)e * 1024 + lane * 16;
;     float f[16];
; #pragma unroll
;     for (int k = 0; k < 4; ++k) { const float4 a = reinterpret_cast<const float4*>(src)[k]; f[4 * k] = a.x; f[4 * k + 1] = a.y; f[4 * k + 2] = a.z; f[4 * k + 3] = a.w; }
;     float am = 0.f;
; #pragma unroll
;     for (int k = 0; k < 16; ++k) am = fmaxf(am, fabsf(f[k]));
;     am = wave_max(am);
;     const float inv = am > 0.f ? 127.f / am : 0.f;
;     unsigned w[4];
; #pragma unroll
;     for (int k = 0; k < 4; ++k) {
;       unsigned pk = 0;
; #pragma unroll
;       for (int b = 0; b < 4; ++b) { int q = (int)rintf(f[4 * k + b] * inv); q = q > 127 ? 127 : (q < -127 ? -127 : q); pk |= ((unsigned)((isv ? q + 128 : q) & 0xff)) << (8 * b); }
;       w[k] = pk;
;     }
;     *reinterpret_cast<uint4*>(ws + (isv ? OFF_VQ + ((long)(lane >> 3) * 16384 + e) * 128 + (lane & 7) * 16 : OFF_UQ + (long)e * 1024 + lane * 16)) = make_uint4(w[0], w[1], w[2], w[3]);
;     if (lane == 0) reinterpret_cast<float*>(ws + (isv ? OFF_VS : OFF_US))[e] = am * (1.f / 127.f);
;   }
.LBB0_944:
	s_or_b64 exec, exec, s[0:1]
	s_add_u32 s38, s78, 0x8000000
	s_addc_u32 s39, s79, 0
	s_cmp_gt_i32 s75, 63
	s_waitcnt lgkmcnt(0)
	s_barrier
	s_cbranch_scc1 .LBB0_949
	s_bitcmp1_b32 s74, 3
	s_cbranch_scc0 .Lp6t_skip
	s_mov_b64 s[26:27], s[18:19]
	s_mov_b64 s[28:29], s[20:21]
	s_mov_b64 s[30:31], exec
	v_readlane_b32 s12, v254, 8
	v_lshlrev_b32_e32 v16, 4, v208
	v_cmp_eq_u32_e64 s[6:7], 0, v208
	v_and_b32_e32 v0, 12, v172
	v_lshl_add_u32 v0, s74, 3, v0
	v_or_b32_e32 v210, v0, v194
	s_lshl_b32 s12, s12, 3
	v_lshlrev_b32_e32 v0, 11, v189
	v_readlane_b32 s16, v254, 0
	v_mov_b32_e32 v19, 0
	v_and_b32_e32 v17, 0x1c000, v0
	v_and_b32_e32 v0, 0x70, v209
	v_readlane_b32 s17, v254, 1
	v_readlane_b32 s18, v254, 2
	v_readlane_b32 s19, v254, 3
	v_or_b32_e32 v24, 0x1000000, v0
	s_mov_b64 s[14:15], 0
	s_movk_i32 s2, 0x4000
	s_movk_i32 s4, 0x3fff
	v_mov_b32_e32 v25, s17
	v_mov_b32_e32 v26, s19
	v_mov_b32_e32 v27, s16
	v_mov_b32_e32 v28, s18
	v_lshlrev_b32_e32 v20, 2, v16
	v_mov_b32_e32 v21, v19
	s_mov_b32 s5, 0x42fe0000
	s_movk_i32 s13, 0xff81
	s_movk_i32 s16, 0xff
	s_movk_i32 s17, 0x4fff
	v_mov_b32_e32 v29, 0x7f
	v_mov_b32_e32 v30, v210
	v_readlane_b32 s20, v254, 4
	v_readlane_b32 s21, v254, 5
	v_readlane_b32 s22, v254, 6
	v_readlane_b32 s23, v254, 7
	v_mov_b32_e32 v148, v30
	v_and_b32_e32 v149, 0x3fff, v148
	v_cmp_lt_i32_e64 s[32:33], s4, v148
	v_lshlrev_b32_e32 v150, 12, v149
	v_mov_b32_e32 v151, 0
	s_nop 0
	v_cndmask_b32_e64 v153, v25, v26, s[32:33]
	v_cndmask_b32_e64 v152, v27, v28, s[32:33]
	v_lshl_add_u64 v[152:153], v[152:153], 0, v[150:151]
	v_lshl_add_u64 v[152:153], v[152:153], 0, v[20:21]
	global_load_dwordx4 v[132:135], v[152:153], off
	global_load_dwordx4 v[136:139], v[152:153], off offset:16
	global_load_dwordx4 v[140:143], v[152:153], off offset:32
	global_load_dwordx4 v[144:147], v[152:153], off offset:48
	s_waitcnt vmcnt(0)
	s_branch .Lp6t1_loop

; DI void phase7(const Params& P, char* smem) {
;     ...
;   for (int row = VB * 4 + wid; row < 2 * 16384; row += NVB * 4) {
;     const bool isv = row >= 16384; const int e = row & 16383;
;     const float* src = (isv ? P.pv : P.pu) + (long)e * 1024 + lane * 16;
;     float f[16];
; #pragma unroll
;     for (int k = 0; k < 4; ++k) { const float4 a = reinterpret_cast<const float4*>(src)[k]; f[4 * k] = a.x; f[4 * k + 1] = a.y; f[4 * k + 2] = a.z; f[4 * k + 3] = a.w; }
;     float am = 0.f;
; #pragma unroll
;     for (int k = 0; k < 16; ++k) am = fmaxf(am, fabsf(f[k]));
;     am = wave_max(am);
;     const float inv = am > 0.f ? 127.f / am : 0.f;
;     unsigned w[4];
; #pragma unroll
;     for (int k = 0; k < 4; ++k) {
;       unsigned pk = 0;
; #pragma unroll
;       for (int b = 0; b < 4; ++b) { int q = (int)rintf(f[4 * k + b] * inv); q = q > 127 ? 127 : (q < -127 ? -127 : q); pk |= ((unsigned)((isv ? q + 128 : q) & 0xff)) << (8 * b); }
;       w[k] = pk;
;     }
;     *reinterpret_cast<uint4*>(ws + (isv ? OFF_VQ + ((long)(lane >> 3) * 16384 + e) * 128 + (lane & 7) * 16 : OFF_UQ + (long)e * 1024 + lane * 16)) = make_uint4(w[0], w[1], w[2], w[3]);
;     if (lane == 0) reinterpret_cast<float*>(ws + (isv ? OFF_VS : OFF_US))[e] = am * (1.f / 127.f);
;   }
.Lp6t1_done:
	s_mov_b64 exec, s[30:31]
	s_waitcnt vmcnt(0)
	v_add_u32_e32 v210, 0xffffffc0, v210
	v_lshlrev_b32_e32 v0, 11, v189
	v_readlane_b32 s16, v254, 0
	v_mov_b32_e32 v19, 0
	v_and_b32_e32 v17, 0x1c000, v0
	v_and_b32_e32 v0, 0x70, v209
	v_readlane_b32 s17, v254, 1
	v_readlane_b32 s18, v254, 2
	v_readlane_b32 s19, v254, 3
	v_or_b32_e32 v24, 0x1000000, v0
	s_mov_b64 s[14:15], 0
	s_movk_i32 s2, 0x4000
	s_movk_i32 s4, 0x3fff
	v_mov_b32_e32 v25, s17
	v_mov_b32_e32 v26, s19
	v_mov_b32_e32 v27, s16
	v_mov_b32_e32 v28, s18
	v_lshlrev_b32_e32 v20, 2, v16
	v_mov_b32_e32 v21, v19
	s_mov_b32 s5, 0x42fe0000
	s_movk_i32 s13, 0xff81
	s_movk_i32 s16, 0xff
	s_movk_i32 s17, 0x4fff
	v_mov_b32_e32 v29, 0x7f
	v_mov_b32_e32 v30, v210
	v_readlane_b32 s20, v254, 4
	v_readlane_b32 s21, v254, 5
	v_readlane_b32 s22, v254, 6
	v_readlane_b32 s23, v254, 7
	v_mov_b32_e32 v148, v30
	v_and_b32_e32 v149, 0x3fff, v148
	v_cmp_lt_i32_e64 s[32:33], s4, v148
	v_lshlrev_b32_e32 v150, 12, v149
	v_mov_b32_e32 v151, 0
	s_nop 0
	v_cndmask_b32_e64 v153, v25, v26, s[32:33]
	v_cndmask_b32_e64 v152, v27, v28, s[32:33]
	v_lshl_add_u64 v[152:153], v[152:153], 0, v[150:151]
	v_lshl_add_u64 v[152:153], v[152:153], 0, v[20:21]
	global_load_dwordx4 v[132:135], v[152:153], off
	global_load_dwordx4 v[136:139], v[152:153], off offset:16
	global_load_dwordx4 v[140:143], v[152:153], off offset:32
	global_load_dwordx4 v[144:147], v[152:153], off offset:48
	s_waitcnt vmcnt(0)
	s_branch .Lp6t2_loop

; DI void phase7(const Params& P, char* smem) {
;     ...
;   for (int row = VB * 4 + wid; row < 2 * 16384; row += NVB * 4) {
;     const bool isv = row >= 16384; const int e = row & 16383;
;     const float* src = (isv ? P.pv : P.pu) + (long)e * 1024 + lane * 16;
;     float f[16];
; #pragma unroll
;     for (int k = 0; k < 4; ++k) { const float4 a = reinterpret_cast<const float4*>(src)[k]; f[4 * k] = a.x; f[4 * k + 1] = a.y; f[4 * k + 2] = a.z; f[4 * k + 3] = a.w; }
;     float am = 0.f;
; #pragma unroll
;     for (int k = 0; k < 16; ++k) am = fmaxf(am, fabsf(f[k]));
;     am = wave_max(am);
;     const float inv = am > 0.f ? 127.f / am : 0.f;
;     unsigned w[4];
; #pragma unroll
;     for (int k = 0; k < 4; ++k) {
;       unsigned pk = 0;
; #pragma unroll
;       for (int b = 0; b < 4; ++b) { int q = (int)rintf(f[4 * k + b] * inv); q = q > 127 ? 127 : (q < -127 ? -127 : q); pk |= ((unsigned)((isv ? q + 128 : q) & 0xff)) << (8 * b); }
;       w[k] = pk;
;     }
;     *reinterpret_cast<uint4*>(ws + (isv ? OFF_VQ + ((long)(lane >> 3) * 16384 + e) * 128 + (lane & 7) * 16 : OFF_UQ + (long)e * 1024 + lane * 16)) = make_uint4(w[0], w[1], w[2], w[3]);
;     if (lane == 0) reinterpret_cast<float*>(ws + (isv ? OFF_VS : OFF_US))[e] = am * (1.f / 127.f);
;   }
.LBB0_949:
	s_bitcmp1_b32 s74, 3
	s_cbranch_scc1 .Lp6u_skip
	s_mov_b64 s[26:27], s[16:17]
	s_mov_b64 s[28:29], s[18:19]
	s_mov_b64 s[30:31], s[20:21]
	s_mov_b64 s[34:35], exec
	v_readlane_b32 s12, v254, 8
	v_lshlrev_b32_e32 v16, 4, v208
	v_cmp_eq_u32_e64 s[6:7], 0, v208
	v_and_b32_e32 v0, 12, v172
	v_lshl_add_u32 v0, s74, 3, v0
	v_or_b32_e32 v210, v0, v194
	s_lshl_b32 s12, s12, 3
	v_lshlrev_b32_e32 v0, 11, v189
	v_readlane_b32 s16, v254, 0
	v_mov_b32_e32 v19, 0
	v_and_b32_e32 v17, 0x1c000, v0
	v_and_b32_e32 v0, 0x70, v209
	v_readlane_b32 s17, v254, 1
	v_readlane_b32 s18, v254, 2
	v_readlane_b32 s19, v254, 3
	v_or_b32_e32 v24, 0x1000000, v0
	s_mov_b64 s[14:15], 0
	s_movk_i32 s2, 0x4000
	s_movk_i32 s4, 0x3fff
	v_mov_b32_e32 v25, s17
	v_mov_b32_e32 v26, s19
	v_mov_b32_e32 v27, s16
	v_mov_b32_e32 v28, s18
	v_lshlrev_b32_e32 v20, 2, v16
	v_mov_b32_e32 v21, v19
	s_mov_b32 s5, 0x42fe0000
	s_movk_i32 s13, 0xff81
	s_movk_i32 s16, 0xff
	s_movk_i32 s17, 0x7fff
	v_mov_b32_e32 v29, 0x7f
	v_add_u32_e32 v30, 0x5000, v210
	v_readlane_b32 s20, v254, 4
	v_readlane_b32 s21, v254, 5
	v_readlane_b32 s22, v254, 6
	v_readlane_b32 s23, v254, 7
	v_mov_b32_e32 v148, v30
	v_and_b32_e32 v149, 0x3fff, v148
	v_cmp_lt_i32_e64 s[32:33], s4, v148
	v_lshlrev_b32_e32 v150, 12, v149
	v_mov_b32_e32 v151, 0
	s_nop 0
	v_cndmask_b32_e64 v153, v25, v26, s[32:33]
	v_cndmask_b32_e64 v152, v27, v28, s[32:33]
	v_lshl_add_u64 v[152:153], v[152:153], 0, v[150:151]
	v_lshl_add_u64 v[152:153], v[152:153], 0, v[20:21]
	global_load_dwordx4 v[132:135], v[152:153], off
	global_load_dwordx4 v[136:139], v[152:153], off offset:16
	global_load_dwordx4 v[140:143], v[152:153], off offset:32
	global_load_dwordx4 v[144:147], v[152:153], off offset:48
	s_waitcnt vmcnt(0)
	s_branch .Lp6u1_loop

; DI void phase7(const Params& P, char* smem) {
;     ...
;   for (int row = VB * 4 + wid; row < 2 * 16384; row += NVB * 4) {
;     const bool isv = row >= 16384; const int e = row & 16383;
;     const float* src = (isv ? P.pv : P.pu) + (long)e * 1024 + lane * 16;
;     float f[16];
; #pragma unroll
;     for (int k = 0; k < 4; ++k) { const float4 a = reinterpret_cast<const float4*>(src)[k]; f[4 * k] = a.x; f[4 * k + 1] = a.y; f[4 * k + 2] = a.z; f[4 * k + 3] = a.w; }
;     float am = 0.f;
; #pragma unroll
;     for (int k = 0; k < 16; ++k) am = fmaxf(am, fabsf(f[k]));
;     am = wave_max(am);
;     const float inv = am > 0.f ? 127.f / am : 0.f;
;     unsigned w[4];
; #pragma unroll
;     for (int k = 0; k < 4; ++k) {
;       unsigned pk = 0;
; #pragma unroll
;       for (int b = 0; b < 4; ++b) { int q = (int)rintf(f[4 * k + b] * inv); q = q > 127 ? 127 : (q < -127 ? -127 : q); pk |= ((unsigned)((isv ? q + 128 : q) & 0xff)) << (8 * b); }
;       w[k] = pk;
;     }
;     *reinterpret_cast<uint4*>(ws + (isv ? OFF_VQ + ((long)(lane >> 3) * 16384 + e) * 128 + (lane & 7) * 16 : OFF_UQ + (long)e * 1024 + lane * 16)) = make_uint4(w[0], w[1], w[2], w[3]);
;     if (lane == 0) reinterpret_cast<float*>(ws + (isv ? OFF_VS : OFF_US))[e] = am * (1.f / 127.f);
;   }
.Lp6u1_done:
	s_mov_b64 exec, s[34:35]
	s_waitcnt vmcnt(0)
	v_add_u32_e32 v210, 64, v210
	v_lshlrev_b32_e32 v0, 11, v189
	v_readlane_b32 s16, v254, 0
	v_mov_b32_e32 v19, 0
	v_and_b32_e32 v17, 0x1c000, v0
	v_and_b32_e32 v0, 0x70, v209
	v_readlane_b32 s17, v254, 1
	v_readlane_b32 s18, v254, 2
	v_readlane_b32 s19, v254, 3
	v_or_b32_e32 v24, 0x1000000, v0
	s_mov_b64 s[14:15], 0
	s_movk_i32 s2, 0x4000
	s_movk_i32 s4, 0x3fff
	v_mov_b32_e32 v25, s17
	v_mov_b32_e32 v26, s19
	v_mov_b32_e32 v27, s16
	v_mov_b32_e32 v28, s18
	v_lshlrev_b32_e32 v20, 2, v16
	v_mov_b32_e32 v21, v19
	s_mov_b32 s5, 0x42fe0000
	s_movk_i32 s13, 0xff81
	s_movk_i32 s16, 0xff
	s_movk_i32 s17, 0x7fff
	v_mov_b32_e32 v29, 0x7f
	v_add_u32_e32 v30, 0x5000, v210
	v_readlane_b32 s20, v254, 4
	v_readlane_b32 s21, v254, 5
	v_readlane_b32 s22, v254, 6
	v_readlane_b32 s23, v254, 7
	v_mov_b32_e32 v148, v30
	v_and_b32_e32 v149, 0x3fff, v148
	v_cmp_lt_i32_e64 s[32:33], s4, v148
	v_lshlrev_b32_e32 v150, 12, v149
	v_mov_b32_e32 v151, 0
	s_nop 0
	v_cndmask_b32_e64 v153, v25, v26, s[32:33]
	v_cndmask_b32_e64 v152, v27, v28, s[32:33]
	v_lshl_add_u64 v[152:153], v[152:153], 0, v[150:151]
	v_lshl_add_u64 v[152:153], v[152:153], 0, v[20:21]
	global_load_dwordx4 v[132:135], v[152:153], off
	global_load_dwordx4 v[136:139], v[152:153], off offset:16
	global_load_dwordx4 v[140:143], v[152:153], off offset:32
	global_load_dwordx4 v[144:147], v[152:153], off offset:48
	s_waitcnt vmcnt(0)
	s_branch .Lp6u2_loop

; DI void phase7(const Params& P, char* smem) {
;     ...
;   for (int row = VB * 4 + wid; row < 2 * 16384; row += NVB * 4) {
;     const bool isv = row >= 16384; const int e = row & 16383;
;     const float* src = (isv ? P.pv : P.pu) + (long)e * 1024 + lane * 16;
;     float f[16];
; #pragma unroll
;     for (int k = 0; k < 4; ++k) { const float4 a = reinterpret_cast<const float4*>(src)[k]; f[4 * k] = a.x; f[4 * k + 1] = a.y; f[4 * k + 2] = a.z; f[4 * k + 3] = a.w; }
.LBB0_1006:
	s_or_b64 exec, exec, s[20:21]
	s_branch .LBB0_1014
	v_lshlrev_b32_e32 v0, 11, v189
	v_readlane_b32 s16, v254, 0
	v_mov_b32_e32 v19, 0
	v_and_b32_e32 v17, 0x1c000, v0
	v_and_b32_e32 v0, 0x70, v209
	v_readlane_b32 s17, v254, 1
	v_readlane_b32 s18, v254, 2
	v_readlane_b32 s19, v254, 3
	v_or_b32_e32 v24, 0x1000000, v0
	s_mov_b64 s[14:15], 0
	s_movk_i32 s2, 0x4000
	s_movk_i32 s4, 0x3fff
	v_mov_b32_e32 v25, s17
	v_mov_b32_e32 v26, s19
	v_mov_b32_e32 v27, s16
	v_mov_b32_e32 v28, s18
	v_lshlrev_b32_e32 v20, 2, v16
	v_mov_b32_e32 v21, v19
	s_mov_b32 s5, 0x42fe0000
	s_movk_i32 s13, 0xff81
	s_movk_i32 s16, 0xff
	s_movk_i32 s17, 0x7fff
	v_mov_b32_e32 v29, 0x7f
	v_add_u32_e32 v30, 0x5000, v210
	v_readlane_b32 s20, v254, 4
	v_readlane_b32 s21, v254, 5
	v_readlane_b32 s22, v254, 6
	v_readlane_b32 s23, v254, 7
	v_mov_b32_e32 v148, v30
	v_and_b32_e32 v149, 0x3fff, v148
	v_cmp_lt_i32_e64 s[32:33], s4, v148
	v_lshlrev_b32_e32 v150, 12, v149
	v_mov_b32_e32 v151, 0
	s_nop 0
	v_cndmask_b32_e64 v153, v25, v26, s[32:33]
	v_cndmask_b32_e64 v152, v27, v28, s[32:33]
	v_lshl_add_u64 v[152:153], v[152:153], 0, v[150:151]
	v_lshl_add_u64 v[152:153], v[152:153], 0, v[20:21]
	global_load_dwordx4 v[132:135], v[152:153], off
	global_load_dwordx4 v[136:139], v[152:153], off offset:16
	global_load_dwordx4 v[140:143], v[152:153], off offset:32
	global_load_dwordx4 v[144:147], v[152:153], off offset:48
	s_waitcnt vmcnt(0)
	s_branch .LBB0_1008
